# attention unit prologue: compiler-inserted vmcnt(0) behind the counted vmcnt(8)+barrier relaxed to lgkmcnt(0) (the eight younger LDS-DMAs stay in flight under the first QK MFMAs)
# speedup vs baseline: 1.0022x; 1.0022x over previous
; #define LAS __attribute__((address_space(3)))
; __device__ __forceinline__ void attn_phase(const Args& A, LAS unsigned char* lds, int vcu, int G, const int tid) {
;     ...
;     for (int u = vcu; u < 768; u += G) {
;         const int bh = u >> 5, qc = u & 31, b = bh / 6, h = bh % 6;
;         const int qrow = b * SEQ + qc * 128 + qi * 32 + r32;
;         bf16x8 qf[4];
;         { const bf16_t* qp = Q + (size_t)qrow * DQK + h * 128 + c * 64 + hi * 8;
; #pragma unroll
;           for (int d0 = 0; d0 < 4; ++d0) qf[d0] = *(const bf16x8*)(qp + d0 * 16); }
;         AT_DMAK(0, 0); AT_DMAK(1, 1); AT_DMAV(0, 0); AT_DMAK(2, 2); AT_DMAV(1, 1);
;         asm volatile("s_waitcnt vmcnt(8)" ::: "memory"); __builtin_amdgcn_s_barrier(); asm volatile("" ::: "memory");
;         f32x16 o[4];
; #pragma unroll
;         for (int i = 0; i < 4; ++i) o[i] = f32x16{};
;         float mrow = -1e30f, lrow = 0.f;
;         f32x16 sa0 = f32x16{}, sa1 = f32x16{}, sb0, sb1;
; #pragma unroll
;         for (int d0 = 0; d0 < 4; ++d0) {
;             const bf16x8 k0 = *(const LAS bf16x8*)(lds + (kad0 ^ (d0 * 32))), k1 = *(const LAS bf16x8*)(lds + (kad0 ^ (d0 * 32)) + 32 * 256);
;             sa0 = __builtin_amdgcn_mfma_f32_32x32x16_bf16(k0, qf[d0], sa0, 0, 0, 0);
;             sa1 = __builtin_amdgcn_mfma_f32_32x32x16_bf16(k1, qf[d0], sa1, 0, 0, 0); }
;         asm volatile("s_waitcnt vmcnt(4) lgkmcnt(0)" ::: "memory"); __builtin_amdgcn_s_barrier(); asm volatile("" ::: "memory");
.LBB0_840:
	s_ashr_i32 s2, s66, 5
	s_mul_hi_i32 s20, s2, 0x2aaaaaab
	s_lshr_b32 s3, s20, 31
	s_add_i32 s20, s20, s3
	s_mul_i32 s3, s20, 6
	s_sub_i32 s14, s2, s3
	s_lshl_b32 s2, s66, 7
	s_and_b32 s2, s2, 0xf80
	s_lshl_b32 s40, s20, 12
	s_or_b32 s2, s2, s56
	s_or_b32 s38, s2, s40
	v_or_b32_e32 v2, s38, v203
	v_mov_b64_e32 v[0:1], s[16:17]
	s_lshl_b32 s36, s14, 7
	v_mad_i64_i32 v[0:1], s[2:3], v2, s55, v[0:1]
	s_ashr_i32 s37, s36, 31
	v_lshl_add_u64 v[0:1], s[36:37], 1, v[0:1]
	v_lshl_add_u64 v[0:1], s[26:27], 1, v[0:1]
	v_lshl_add_u64 v[0:1], v[0:1], 0, v[190:191]
	s_ashr_i32 s41, s40, 31
	s_mul_i32 s2, s20, 0x600000
	global_load_dwordx4 v[160:163], v[0:1], off
	global_load_dwordx4 v[164:167], v[0:1], off offset:32
	global_load_dwordx4 v[168:171], v[0:1], off offset:64
	global_load_dwordx4 v[172:175], v[0:1], off offset:96
	s_mul_hi_i32 s3, s40, 0x600
	s_add_u32 s2, s53, s2
	s_addc_u32 s3, s54, s3
	s_lshl_b32 s12, s14, 8
	s_ashr_i32 s13, s12, 31
	s_add_u32 s2, s2, s12
	s_addc_u32 s3, s3, s13
	s_mov_b32 m0, s58
	v_lshl_add_u64 v[0:1], s[2:3], 0, v[198:199]
	global_load_lds_dwordx4 v[0:1], off
	v_lshl_add_u64 v[0:1], s[2:3], 0, v[194:195]
	s_or_b32 s2, s40, 64
	s_ashr_i32 s3, s2, 31
	s_mul_i32 s5, s2, 0x600
	s_mul_hi_i32 s4, s2, 0x600
	s_add_u32 s5, s53, s5
	s_addc_u32 s15, s54, s4
	s_add_u32 s4, s5, s12
	s_mov_b32 m0, s64
	s_addc_u32 s5, s15, s13
	global_load_lds_dwordx4 v[0:1], off
	v_lshl_add_u64 v[0:1], s[4:5], 0, v[198:199]
	s_mov_b32 m0, s65
	s_mul_i32 s14, s14, 0x440000
	global_load_lds_dwordx4 v[0:1], off
	s_add_i32 m0, s58, 0x4400
	v_lshl_add_u64 v[0:1], s[4:5], 0, v[194:195]
	s_mul_hi_i32 s4, s36, 0x8800
	s_add_u32 s39, s51, s14
	s_addc_u32 s67, s52, s4
	s_lshl_b64 s[4:5], s[40:41], 1
	s_add_u32 s4, s39, s4
	s_addc_u32 s5, s67, s5
	global_load_lds_dwordx4 v[0:1], off
	v_lshl_add_u64 v[0:1], s[4:5], 0, v[196:197]
	s_add_i32 m0, s58, 0xc000
	s_or_b32 s42, s40, 0x80
	global_load_lds_dwordx4 v[0:1], off
	v_lshl_add_u64 v[0:1], s[4:5], 0, v[192:193]
	s_add_i32 m0, s58, 0xc400
	s_mul_i32 s5, s42, 0x600
	s_mul_hi_i32 s4, s42, 0x600
	s_add_u32 s5, s53, s5
	s_addc_u32 s14, s54, s4
	s_add_u32 s4, s5, s12
	s_addc_u32 s5, s14, s13
	global_load_lds_dwordx4 v[0:1], off
	v_lshl_add_u64 v[0:1], s[4:5], 0, v[198:199]
	s_add_i32 m0, s58, 0x8000
	s_lshl_b64 s[2:3], s[2:3], 1
	global_load_lds_dwordx4 v[0:1], off
	s_add_i32 m0, s58, 0x8400
	s_add_u32 s2, s39, s2
	v_lshl_add_u64 v[0:1], s[4:5], 0, v[194:195]
	s_addc_u32 s3, s67, s3
	s_add_i32 s4, 0, 0x10000
	global_load_lds_dwordx4 v[0:1], off
	v_lshl_add_u64 v[0:1], s[2:3], 0, v[196:197]
	s_add_i32 m0, s4, s57
	v_add_u32_e32 v4, 0, v205
	global_load_lds_dwordx4 v[0:1], off
	v_lshl_add_u64 v[0:1], s[2:3], 0, v[192:193]
	s_add_i32 m0, s4, s59
	s_andn2_b64 vcc, exec, s[28:29]
	global_load_lds_dwordx4 v[0:1], off
	s_waitcnt vmcnt(8)
	s_barrier
	ds_read_b128 v[0:3], v4
	ds_read_b128 v[4:7], v4 offset:8192
	s_waitcnt lgkmcnt(0)
	v_mfma_f32_32x32x16_bf16 v[48:63], v[0:3], v[160:163], 0
	v_mfma_f32_32x32x16_bf16 v[32:47], v[4:7], v[160:163], 0
	ds_read_b128 v[0:3], v211
	ds_read_b128 v[4:7], v211 offset:8192
	s_waitcnt lgkmcnt(1)
	v_mfma_f32_32x32x16_bf16 v[48:63], v[0:3], v[164:167], v[48:63]
	s_waitcnt lgkmcnt(0)
	v_mfma_f32_32x32x16_bf16 v[32:47], v[4:7], v[164:167], v[32:47]
	ds_read_b128 v[0:3], v212
	ds_read_b128 v[4:7], v212 offset:8192
	s_waitcnt lgkmcnt(1)
	v_mfma_f32_32x32x16_bf16 v[48:63], v[0:3], v[168:171], v[48:63]
	s_waitcnt lgkmcnt(0)
	v_mfma_f32_32x32x16_bf16 v[32:47], v[4:7], v[168:171], v[32:47]
	ds_read_b128 v[0:3], v213
	ds_read_b128 v[4:7], v213 offset:8192
	s_waitcnt vmcnt(4) lgkmcnt(0)
	s_barrier
	s_waitcnt lgkmcnt(1)
	v_mfma_f32_32x32x16_bf16 v[48:63], v[0:3], v[172:175], v[48:63]
	v_cndmask_b32_e64 v0, 0, 1, s[28:29]
	v_cmp_ne_u32_e64 s[4:5], 1, v0
	s_waitcnt lgkmcnt(0)
	v_mfma_f32_32x32x16_bf16 v[32:47], v[4:7], v[172:175], v[32:47]
	s_cbranch_vccnz .LBB0_842
	s_setprio 3
